# restore 2-wait-state spacing before DPP adds in the scan loop (s_nop where SALU was removed)
# baseline (speedup 1.0000x reference)
.LBB0_568:
	s_waitcnt lgkmcnt(1)
	v_pk_fma_f32 v[78:79], v[22:23], v[4:5], 0 op_sel_hi:[1,1,0]
	v_pk_fma_f32 v[4:5], v[30:31], v[4:5], 0 op_sel_hi:[1,1,0]
	v_pk_fma_f32 v[78:79], v[24:25], v[6:7], v[78:79]
	v_pk_fma_f32 v[4:5], v[32:33], v[6:7], v[4:5]
	s_waitcnt lgkmcnt(0)
	v_pk_fma_f32 v[6:7], v[26:27], v[0:1], v[78:79]
	v_pk_fma_f32 v[0:1], v[34:35], v[0:1], v[4:5]
	v_pk_fma_f32 v[4:5], v[28:29], v[2:3], v[6:7]
	v_pk_fma_f32 v[0:1], v[36:37], v[2:3], v[0:1]
	v_add_f32_e32 v2, v4, v5
	v_add_u32_e32 v80, s50, v44
	v_add_f32_e32 v0, v0, v1
	v_add_f32_dpp v2, v2, v2 quad_perm:[1,0,3,2] row_mask:0xf bank_mask:0xf bound_ctrl:1
	ds_read_b128 v[46:49], v80 offset:256
	ds_read_b128 v[50:53], v80 offset:272
	ds_read_b128 v[54:57], v80 offset:512
	ds_read_b128 v[58:61], v80 offset:768
	ds_read_b128 v[62:65], v80 offset:1024
	ds_read_b128 v[66:69], v80 offset:528
	ds_read_b128 v[70:73], v80 offset:784
	ds_read_b128 v[74:77], v80 offset:1040
	v_add_f32_dpp v2, v2, v2 quad_perm:[2,3,0,1] row_mask:0xf bank_mask:0xf bound_ctrl:1
	v_add_f32_dpp v0, v0, v0 quad_perm:[1,0,3,2] row_mask:0xf bank_mask:0xf bound_ctrl:1
	s_waitcnt lgkmcnt(7)
	v_pk_mul_f32 v[4:5], v[22:23], v[46:47]
	v_add_f32_dpp v2, v2, v2 row_half_mirror row_mask:0xf bank_mask:0xf bound_ctrl:1
	v_add_f32_dpp v0, v0, v0 quad_perm:[2,3,0,1] row_mask:0xf bank_mask:0xf bound_ctrl:1
	s_waitcnt lgkmcnt(5)
	v_pk_fma_f32 v[4:5], v[54:55], v[2:3], v[4:5] op_sel_hi:[1,0,1] neg_lo:[0,1,0] neg_hi:[0,1,0]
	v_pk_mul_f32 v[24:25], v[24:25], v[48:49]
	v_add_f32_dpp v0, v0, v0 row_half_mirror row_mask:0xf bank_mask:0xf bound_ctrl:1
	s_waitcnt lgkmcnt(4)
	v_pk_fma_f32 v[22:23], v[58:59], v[38:39], v[4:5] op_sel_hi:[1,0,1]
	v_pk_mul_f32 v[4:5], v[30:31], v[46:47]
	v_pk_mul_f32 v[32:33], v[32:33], v[48:49]
	v_pk_fma_f32 v[4:5], v[54:55], v[0:1], v[4:5] op_sel_hi:[1,0,1] neg_lo:[0,1,0] neg_hi:[0,1,0]
	v_pk_mul_f32 v[26:27], v[26:27], v[50:51]
	v_pk_mul_f32 v[28:29], v[28:29], v[52:53]
	v_add_u32_e32 v8, s39, v45
	v_pk_fma_f32 v[30:31], v[58:59], v[38:39], v[4:5] op_sel:[0,1,0]
	v_pk_fma_f32 v[24:25], v[56:57], v[2:3], v[24:25] op_sel_hi:[1,0,1] neg_lo:[0,1,0] neg_hi:[0,1,0]
	v_pk_fma_f32 v[32:33], v[56:57], v[0:1], v[32:33] op_sel_hi:[1,0,1] neg_lo:[0,1,0] neg_hi:[0,1,0]
	s_waitcnt lgkmcnt(2)
	v_pk_fma_f32 v[26:27], v[66:67], v[2:3], v[26:27] op_sel_hi:[1,0,1] neg_lo:[0,1,0] neg_hi:[0,1,0]
	v_pk_mul_f32 v[34:35], v[34:35], v[50:51]
	v_pk_fma_f32 v[2:3], v[68:69], v[2:3], v[28:29] op_sel_hi:[1,0,1] neg_lo:[0,1,0] neg_hi:[0,1,0]
	ds_read_b128 v[16:19], v80 offset:1552
	ds_read_b128 v[12:15], v80 offset:1568
	ds_read2_b64 v[8:11], v8 offset1:194
	v_pk_fma_f32 v[4:5], v[22:23], v[62:63], 0 op_sel_hi:[1,1,0]
	v_pk_fma_f32 v[6:7], v[30:31], v[62:63], 0 op_sel_hi:[1,1,0]
	v_pk_fma_f32 v[24:25], v[60:61], v[38:39], v[24:25] op_sel_hi:[1,0,1]
	v_pk_fma_f32 v[32:33], v[60:61], v[38:39], v[32:33] op_sel:[0,1,0]
	v_pk_fma_f32 v[34:35], v[66:67], v[0:1], v[34:35] op_sel_hi:[1,0,1] neg_lo:[0,1,0] neg_hi:[0,1,0]
	s_waitcnt lgkmcnt(4)
	v_pk_fma_f32 v[28:29], v[72:73], v[38:39], v[2:3] op_sel_hi:[1,0,1]
	v_pk_mul_f32 v[2:3], v[36:37], v[52:53]
	v_pk_fma_f32 v[4:5], v[24:25], v[64:65], v[4:5]
	v_pk_fma_f32 v[6:7], v[32:33], v[64:65], v[6:7]
	v_pk_fma_f32 v[26:27], v[70:71], v[38:39], v[26:27] op_sel_hi:[1,0,1]
	v_pk_fma_f32 v[34:35], v[70:71], v[38:39], v[34:35] op_sel:[0,1,0]
	v_pk_fma_f32 v[0:1], v[68:69], v[0:1], v[2:3] op_sel_hi:[1,0,1] neg_lo:[0,1,0] neg_hi:[0,1,0]
	s_waitcnt lgkmcnt(3)
	v_pk_fma_f32 v[4:5], v[26:27], v[74:75], v[4:5]
	v_pk_fma_f32 v[6:7], v[34:35], v[74:75], v[6:7]
	v_pk_fma_f32 v[36:37], v[72:73], v[38:39], v[0:1] op_sel:[0,1,0]
	v_pk_fma_f32 v[0:1], v[28:29], v[76:77], v[4:5]
	v_pk_fma_f32 v[2:3], v[36:37], v[76:77], v[6:7]
	s_waitcnt lgkmcnt(2)
	v_pk_fma_f32 v[38:39], v[22:23], v[16:17], 0 op_sel_hi:[1,1,0]
	v_add_f32_e32 v0, v0, v1
	v_add_f32_e32 v1, v2, v3
	v_pk_fma_f32 v[16:17], v[30:31], v[16:17], 0 op_sel_hi:[1,1,0]
	v_pk_fma_f32 v[38:39], v[24:25], v[18:19], v[38:39]
	v_add_f32_dpp v0, v0, v0 quad_perm:[1,0,3,2] row_mask:0xf bank_mask:0xf bound_ctrl:1
	v_add_f32_dpp v1, v1, v1 quad_perm:[1,0,3,2] row_mask:0xf bank_mask:0xf bound_ctrl:1
	v_pk_fma_f32 v[16:17], v[32:33], v[18:19], v[16:17]
	s_waitcnt lgkmcnt(1)
; __device__ __forceinline__ void scan_unit(const Params& p, int l, int u, unsigned char* lds) {
;     ...
; #pragma unroll 1
;             for (int sl = 0; sl < CHUNK; sl += 2) {
;                 SCAN_STEP(ha, hb, sl)
;                 SCAN_STEP(hb, ha, sl + 1)
;             }
;             __syncthreads();
	v_pk_fma_f32 v[18:19], v[26:27], v[12:13], v[38:39]
	v_add_f32_dpp v0, v0, v0 quad_perm:[2,3,0,1] row_mask:0xf bank_mask:0xf bound_ctrl:1
	v_add_f32_dpp v1, v1, v1 quad_perm:[2,3,0,1] row_mask:0xf bank_mask:0xf bound_ctrl:1
	v_pk_fma_f32 v[12:13], v[34:35], v[12:13], v[16:17]
	v_pk_fma_f32 v[16:17], v[28:29], v[14:15], v[18:19]
	v_add_f32_dpp v0, v0, v0 row_half_mirror row_mask:0xf bank_mask:0xf bound_ctrl:1
	v_add_f32_dpp v1, v1, v1 row_half_mirror row_mask:0xf bank_mask:0xf bound_ctrl:1
	v_pk_fma_f32 v[12:13], v[36:37], v[14:15], v[12:13]
	v_add_f32_e32 v14, v16, v17
	v_cvt_pk_bf16_f32 v2, v0, v1
	global_store_dword v[20:21], v2, off
	v_lshl_add_u64 v[20:21], v[20:21], 0, s[78:79]
	v_add_f32_dpp v14, v14, v14 quad_perm:[1,0,3,2] row_mask:0xf bank_mask:0xf bound_ctrl:1
	v_add_f32_e32 v12, v12, v13
	ds_read_b128 v[46:49], v80 offset:1808
	ds_read_b128 v[50:53], v80 offset:2064
	ds_read_b128 v[54:57], v80 offset:2320
	ds_read_b128 v[58:61], v80 offset:2576
	ds_read_b128 v[62:65], v80 offset:1824
	ds_read_b128 v[66:69], v80 offset:2080
	ds_read_b128 v[70:73], v80 offset:2336
	ds_read_b128 v[74:77], v80 offset:2592
	ds_read_b128 v[4:7], v80 offset:3104
	ds_read_b128 v[0:3], v80 offset:3120
	v_add_f32_dpp v14, v14, v14 quad_perm:[2,3,0,1] row_mask:0xf bank_mask:0xf bound_ctrl:1
	v_add_f32_dpp v12, v12, v12 quad_perm:[1,0,3,2] row_mask:0xf bank_mask:0xf bound_ctrl:1
	s_waitcnt lgkmcnt(9)
	v_pk_mul_f32 v[16:17], v[22:23], v[46:47]
	v_add_f32_dpp v14, v14, v14 row_half_mirror row_mask:0xf bank_mask:0xf bound_ctrl:1
	v_add_f32_dpp v12, v12, v12 quad_perm:[2,3,0,1] row_mask:0xf bank_mask:0xf bound_ctrl:1
	s_waitcnt lgkmcnt(8)
	v_pk_fma_f32 v[16:17], v[50:51], v[14:15], v[16:17] op_sel_hi:[1,0,1] neg_lo:[0,1,0] neg_hi:[0,1,0]
	v_pk_mul_f32 v[24:25], v[24:25], v[48:49]
	v_add_f32_dpp v12, v12, v12 row_half_mirror row_mask:0xf bank_mask:0xf bound_ctrl:1
	s_waitcnt lgkmcnt(7)
	v_pk_fma_f32 v[22:23], v[54:55], v[8:9], v[16:17] op_sel_hi:[1,0,1]
	v_pk_mul_f32 v[16:17], v[30:31], v[46:47]
	v_pk_mul_f32 v[32:33], v[32:33], v[48:49]
	v_pk_fma_f32 v[16:17], v[50:51], v[12:13], v[16:17] op_sel_hi:[1,0,1] neg_lo:[0,1,0] neg_hi:[0,1,0]
	s_waitcnt lgkmcnt(5)
	v_pk_mul_f32 v[26:27], v[26:27], v[62:63]
	v_pk_mul_f32 v[28:29], v[28:29], v[64:65]
	v_pk_fma_f32 v[30:31], v[54:55], v[8:9], v[16:17] op_sel:[0,1,0]
	v_pk_fma_f32 v[24:25], v[52:53], v[14:15], v[24:25] op_sel_hi:[1,0,1] neg_lo:[0,1,0] neg_hi:[0,1,0]
	v_pk_fma_f32 v[32:33], v[52:53], v[12:13], v[32:33] op_sel_hi:[1,0,1] neg_lo:[0,1,0] neg_hi:[0,1,0]
	s_waitcnt lgkmcnt(4)
	v_pk_fma_f32 v[26:27], v[66:67], v[14:15], v[26:27] op_sel_hi:[1,0,1] neg_lo:[0,1,0] neg_hi:[0,1,0]
	v_pk_mul_f32 v[34:35], v[34:35], v[62:63]
	v_pk_fma_f32 v[14:15], v[68:69], v[14:15], v[28:29] op_sel_hi:[1,0,1] neg_lo:[0,1,0] neg_hi:[0,1,0]
	v_pk_fma_f32 v[16:17], v[22:23], v[58:59], 0 op_sel_hi:[1,1,0]
	v_pk_fma_f32 v[18:19], v[30:31], v[58:59], 0 op_sel_hi:[1,1,0]
	v_pk_fma_f32 v[24:25], v[56:57], v[8:9], v[24:25] op_sel_hi:[1,0,1]
	v_pk_fma_f32 v[32:33], v[56:57], v[8:9], v[32:33] op_sel:[0,1,0]
	v_pk_fma_f32 v[34:35], v[66:67], v[12:13], v[34:35] op_sel_hi:[1,0,1] neg_lo:[0,1,0] neg_hi:[0,1,0]
	s_waitcnt lgkmcnt(3)
	v_pk_fma_f32 v[28:29], v[72:73], v[8:9], v[14:15] op_sel_hi:[1,0,1]
	v_pk_mul_f32 v[14:15], v[36:37], v[64:65]
	v_pk_fma_f32 v[16:17], v[24:25], v[60:61], v[16:17]
	v_pk_fma_f32 v[18:19], v[32:33], v[60:61], v[18:19]
	v_pk_fma_f32 v[26:27], v[70:71], v[8:9], v[26:27] op_sel_hi:[1,0,1]
	v_pk_fma_f32 v[34:35], v[70:71], v[8:9], v[34:35] op_sel:[0,1,0]
	v_pk_fma_f32 v[12:13], v[68:69], v[12:13], v[14:15] op_sel_hi:[1,0,1] neg_lo:[0,1,0] neg_hi:[0,1,0]
	s_waitcnt lgkmcnt(2)
	v_pk_fma_f32 v[16:17], v[26:27], v[74:75], v[16:17]
	v_pk_fma_f32 v[18:19], v[34:35], v[74:75], v[18:19]
	v_pk_fma_f32 v[36:37], v[72:73], v[8:9], v[12:13] op_sel:[0,1,0]
	v_pk_fma_f32 v[8:9], v[28:29], v[76:77], v[16:17]
	v_pk_fma_f32 v[12:13], v[36:37], v[76:77], v[18:19]
	v_add_f32_e32 v8, v8, v9
	v_add_f32_e32 v9, v12, v13
	s_nop 0
	v_add_f32_dpp v8, v8, v8 quad_perm:[1,0,3,2] row_mask:0xf bank_mask:0xf bound_ctrl:1
	v_add_f32_dpp v9, v9, v9 quad_perm:[1,0,3,2] row_mask:0xf bank_mask:0xf bound_ctrl:1
	s_nop 0
	v_add_f32_dpp v8, v8, v8 quad_perm:[2,3,0,1] row_mask:0xf bank_mask:0xf bound_ctrl:1
	v_add_f32_dpp v9, v9, v9 quad_perm:[2,3,0,1] row_mask:0xf bank_mask:0xf bound_ctrl:1
	s_nop 0
	v_add_f32_dpp v8, v8, v8 row_half_mirror row_mask:0xf bank_mask:0xf bound_ctrl:1
	v_add_f32_dpp v9, v9, v9 row_half_mirror row_mask:0xf bank_mask:0xf bound_ctrl:1
	s_add_i32 s77, s76, 2
	s_addk_i32 s50, 0xc20
	v_cvt_pk_bf16_f32 v12, v8, v9
	v_add_u32_e32 v45, 0xc20, v45
	s_cmp_gt_u32 s76, 29
	s_mov_b32 s76, s77
	v_mov_b64_e32 v[38:39], v[10:11]
	global_store_dword v[20:21], v12, off
	v_lshl_add_u64 v[20:21], v[20:21], 0, s[78:79]
	s_cbranch_scc0 .LBB0_568
	s_add_i32 s28, s28, 1
	s_add_i32 s18, s18, 32
	s_sub_i32 s5, s5, 32
	v_add_u32_e32 v42, 0xc200, v42
	s_cmpk_eq_i32 s28, 8
	s_cselect_b32 s76, 0x240000, 0
	s_cmp_lg_u64 s[2:3], 0
	s_cselect_b32 s76, 0, s76
	s_mov_b32 s77, 0
	v_lshl_add_u64 v[20:21], v[20:21], 0, s[76:77]
	s_cmpk_eq_i32 s28, 0x48
	v_add_u32_e32 v43, 0xc200, v43
	s_waitcnt lgkmcnt(0)
	s_barrier
	s_cbranch_scc0 .LBB0_567
	s_branch .LBB0_517
